# speedup vs baseline: 1.0225x; 1.0019x over previous
; __device__ __forceinline__ unsigned pk2(float a, float b) { f2_t x; x[0] = a; x[1] = b; return __builtin_bit_cast(unsigned, __builtin_convertvector(x, bf2_t)); }
; __device__ __forceinline__ float b2f(u16 b) { return __uint_as_float(((unsigned)b) << 16); }
; __device__ __forceinline__ void post_phase(const Params& p, int j, u16* Y, const u16* V, const u16* YB) {
;     ...
;       unsigned bw_ = bon[(size_t)tok * 16 + hd];
;       float bonus = b2f((u16)(bw_ & 0xffffu)) + b2f((u16)(bw_ >> 16));
;       float yv[4][4], s1 = 0.f;
;       _Pragma("unroll") for (int m = 0; m < 4; ++m) {
;         yv[m][0] = b2f((u16)(yr[m].x & 0xffffu)) + b2f((u16)(yb2[m].x & 0xffffu)); yv[m][1] = b2f((u16)(yr[m].x >> 16)) + b2f((u16)(yb2[m].x >> 16));
;         yv[m][2] = b2f((u16)(yr[m].y & 0xffffu)) + b2f((u16)(yb2[m].y & 0xffffu)); yv[m][3] = b2f((u16)(yr[m].y >> 16)) + b2f((u16)(yb2[m].y >> 16));
;         s1 += yv[m][0] + yv[m][1] + yv[m][2] + yv[m][3];
;       }
;       s1 += shx(s1, 16, lane); s1 += shx(s1, 32, lane);
;       float mu = s1 * (1.f / 64.f), s2 = 0.f;
;       _Pragma("unroll") for (int m = 0; m < 4; ++m) _Pragma("unroll") for (int e = 0; e < 4; ++e) { float dd = yv[m][e] - mu; s2 += dd * dd; }
;       s2 += shx(s2, 16, lane); s2 += shx(s2, 32, lane);
;       float rsd = rsqrtf(s2 * (1.f / 64.f) + 64e-5f);
;       _Pragma("unroll") for (int m = 0; m < 4; ++m) {
;         int ch0 = hd * 64 + m * 16;
;         f32x4 g = {0.f, 0.f, 0.f, 0.f};
;         _Pragma("unroll") for (int ks = 0; ks < 5; ++ks) g = MFMA16(ga[m][ks], gb[ks], g);
;         float4 lg4 = *reinterpret_cast<const float4*>(lg + ch0 + fq * 4);
;         float4 lb4 = *reinterpret_cast<const float4*>(lb + ch0 + fq * 4);
;         float vv0 = b2f((u16)(vr[m].x & 0xffffu)), vv1 = b2f((u16)(vr[m].x >> 16));
;         float vv2 = b2f((u16)(vr[m].y & 0xffffu)), vv3 = b2f((u16)(vr[m].y >> 16));
;         float o0 = ((yv[m][0] - mu) * rsd * lg4.x + lb4.x + bonus * vv0) * g[0];
;         float o1 = ((yv[m][1] - mu) * rsd * lg4.y + lb4.y + bonus * vv1) * g[1];
;         float o2 = ((yv[m][2] - mu) * rsd * lg4.z + lb4.z + bonus * vv2) * g[2];
;         float o3 = ((yv[m][3] - mu) * rsd * lg4.w + lb4.w + bonus * vv3) * g[3];
;         uint2 o; o.x = pk2(o0, o1); o.y = pk2(o2, o3);
;         *reinterpret_cast<uint2*>(Y + (size_t)tok * CM + ch0 + fq * 4) = o;
.LBB0_2809:
	v_lshl_add_u64 v[154:155], v[124:125], 2, v[154:155]
	global_load_dword v145, v[154:155], off
	s_waitcnt vmcnt(27)
	v_mfma_f32_16x16x32_bf16 v[96:99], v[96:99], v[16:19], 0
	s_waitcnt vmcnt(16)
	v_lshlrev_b32_e32 v176, 16, v172
	s_waitcnt vmcnt(15)
	v_lshlrev_b32_e32 v178, 16, v168
	v_and_b32_e32 v177, 0xffff0000, v172
	v_mfma_f32_16x16x32_bf16 v[92:95], v[92:95], v[12:15], v[96:99]
	v_and_b32_e32 v179, 0xffff0000, v168
	v_lshlrev_b32_e32 v154, 16, v166
	v_lshlrev_b32_e32 v174, 16, v170
	v_mfma_f32_16x16x32_bf16 v[88:91], v[88:91], v[8:11], v[92:95]
	v_and_b32_e32 v155, 0xffff0000, v166
	v_and_b32_e32 v175, 0xffff0000, v170
	v_pk_add_f32 v[176:177], v[176:177], v[178:179]
	v_mfma_f32_16x16x32_bf16 v[84:87], v[84:87], v[4:7], v[88:91]
	v_lshlrev_b32_e32 v179, 16, v173
	v_lshlrev_b32_e32 v181, 16, v169
	v_and_b32_e32 v178, 0xffff0000, v173
	v_mfma_f32_16x16x32_bf16 v[80:83], v[80:83], v[0:3], v[84:87]
	s_nop 3
	global_load_dwordx4 v[84:87], v[140:141], off
	global_load_dwordx4 v[88:91], v[142:143], off
	global_load_dwordx4 v[202:205], v[140:141], off offset:64
	global_load_dwordx4 v[206:209], v[142:143], off offset:64
	global_load_dwordx4 v[210:213], v[140:141], off offset:128
	global_load_dwordx4 v[214:217], v[142:143], off offset:128
	global_load_dwordx4 v[218:221], v[140:141], off offset:192
	global_load_dwordx4 v[222:225], v[142:143], off offset:192
	v_and_b32_e32 v180, 0xffff0000, v169
	v_lshlrev_b32_e32 v166, 16, v167
	v_lshlrev_b32_e32 v170, 16, v171
	v_and_b32_e32 v167, 0xffff0000, v167
	v_and_b32_e32 v171, 0xffff0000, v171
	v_pk_add_f32 v[168:169], v[178:179], v[180:181]
	v_pk_add_f32 v[172:173], v[176:177], v[176:177] op_sel:[0,1] op_sel_hi:[1,0]
	v_pk_add_f32 v[154:155], v[154:155], v[174:175]
	v_pk_add_f32 v[172:173], v[172:173], v[168:169] op_sel:[0,1] op_sel_hi:[1,0]
	v_pk_add_f32 v[166:167], v[166:167], v[170:171]
	v_add_f32_e32 v94, v154, v155
	v_pk_add_f32 v[96:97], v[168:169], v[172:173]
	s_waitcnt vmcnt(16)
	v_lshlrev_b32_e32 v98, 16, v162
	v_lshlrev_b32_e32 v172, 16, v158
	v_and_b32_e32 v99, 0xffff0000, v162
	v_and_b32_e32 v173, 0xffff0000, v158
	v_add_f32_e32 v94, v94, v166
	v_add_f32_e32 v94, v167, v94
	v_pk_add_f32 v[98:99], v[172:173], v[98:99]
	v_and_b32_e32 v92, 0xffff0000, v163
	s_waitcnt vmcnt(9)
	v_and_b32_e32 v95, 0xffff0000, v160
	v_lshlrev_b32_e32 v93, 16, v161
	v_and_b32_e32 v97, 0xffff0000, v161
	v_add_f32_e32 v158, 0, v94
	v_lshlrev_b32_e32 v171, 16, v164
	v_lshlrev_b32_e32 v170, 16, v159
	v_lshlrev_b32_e32 v161, 16, v160
	v_lshlrev_b32_e32 v160, 16, v163
	v_and_b32_e32 v163, 0xffff0000, v164
	v_mov_b32_e32 v162, v98
	v_mov_b32_e32 v94, v99
	v_pk_add_f32 v[160:161], v[170:171], v[160:161]
	v_and_b32_e32 v170, 0xffff0000, v159
	v_lshlrev_b32_e32 v171, 16, v165
	v_and_b32_e32 v159, 0xffff0000, v165
	v_pk_add_f32 v[94:95], v[162:163], v[94:95]
	v_pk_add_f32 v[92:93], v[170:171], v[92:93]
	v_pk_add_f32 v[96:97], v[158:159], v[96:97]
	v_pk_add_f32 v[158:159], v[160:161], v[94:95]
	v_mfma_f32_16x16x32_bf16 v[76:79], v[76:79], v[16:19], 0
	v_add_f32_e64 v158, v158, v92
	v_add_f32_e64 v159, v159, v93
	s_add_i32 s2, s2, s81
	v_pk_add_f32 v[158:159], v[96:97], v[158:159]
	v_mfma_f32_16x16x32_bf16 v[72:75], v[72:75], v[12:15], v[76:79]
	v_add_f32_e32 v94, v158, v159
	ds_bpermute_b32 v158, v128, v94
	v_mov_b32_e32 v96, v97
	v_mfma_f32_16x16x32_bf16 v[68:71], v[68:71], v[8:11], v[72:75]
	v_mov_b32_e32 v97, v93
	s_cmpk_lt_i32 s2, 0x1800
	s_waitcnt lgkmcnt(0)
	v_add_f32_e32 v76, v94, v158
	ds_bpermute_b32 v77, v193, v76
	v_mov_b32_e32 v73, v92
	v_mov_b32_e32 v72, v160
	v_mov_b32_e32 v160, v95
	v_mfma_f32_16x16x32_bf16 v[64:67], v[64:67], v[16:19], 0
	s_waitcnt lgkmcnt(0)
	v_add_f32_e32 v74, v76, v77
	v_mul_f32_e32 v74, 0x3c800000, v74
	v_pk_add_f32 v[76:77], v[154:155], v[74:75] op_sel_hi:[1,0] neg_lo:[0,1] neg_hi:[0,1]
	v_pk_add_f32 v[92:93], v[166:167], v[74:75] op_sel_hi:[1,0] neg_lo:[0,1] neg_hi:[0,1]
	v_pk_mul_f32 v[78:79], v[76:77], v[76:77]
	v_pk_mul_f32 v[154:155], v[92:93], v[92:93]
	v_add_f32_e32 v78, v78, v79
	v_pk_add_f32 v[164:165], v[168:169], v[74:75] op_sel_hi:[1,0] neg_lo:[0,1] neg_hi:[0,1]
	v_pk_add_f32 v[168:169], v[176:177], v[74:75] op_sel_hi:[1,0] neg_lo:[0,1] neg_hi:[0,1]
	v_add_f32_e32 v78, v154, v78
	v_pk_mul_f32 v[170:171], v[168:169], v[168:169]
	v_add_f32_e32 v78, v155, v78
	v_add_f32_e32 v78, v170, v78
	v_pk_mul_f32 v[166:167], v[164:165], v[164:165]
	v_add_f32_e32 v78, v171, v78
	v_pk_add_f32 v[98:99], v[98:99], v[74:75] op_sel_hi:[1,0] neg_lo:[0,1] neg_hi:[0,1]
	v_add_f32_e32 v78, v167, v78
	v_pk_mul_f32 v[158:159], v[98:99], v[98:99]
	v_add_f32_e32 v78, v166, v78
	v_pk_add_f32 v[72:73], v[72:73], v[74:75] op_sel_hi:[1,0] neg_lo:[0,1] neg_hi:[0,1]
	v_add_f32_e32 v78, v158, v78
	v_pk_add_f32 v[94:95], v[160:161], v[74:75] op_sel_hi:[1,0] neg_lo:[0,1] neg_hi:[0,1]
	v_pk_add_f32 v[96:97], v[96:97], v[74:75] op_sel_hi:[1,0] neg_lo:[0,1] neg_hi:[0,1]
	v_pk_mul_f32 v[74:75], v[72:73], v[72:73]
	v_add_f32_e32 v78, v159, v78
	v_add_f32_e32 v74, v74, v78
	v_pk_mul_f32 v[160:161], v[94:95], v[94:95]
	v_add_f32_e32 v74, v75, v74
	v_add_f32_e32 v74, v161, v74
	v_pk_mul_f32 v[162:163], v[96:97], v[96:97]
	v_add_f32_e32 v74, v160, v74
	v_add_f32_e32 v74, v163, v74
	v_add_f32_e32 v74, v162, v74
	ds_bpermute_b32 v75, v128, v74
	s_waitcnt vmcnt(8)
; __device__ __forceinline__ unsigned pk2(float a, float b) { f2_t x; x[0] = a; x[1] = b; return __builtin_bit_cast(unsigned, __builtin_convertvector(x, bf2_t)); }
; __device__ __forceinline__ float b2f(u16 b) { return __uint_as_float(((unsigned)b) << 16); }
; #define MFMA16(a, b, c) __builtin_amdgcn_mfma_f32_16x16x32_bf16(a, b, c, 0, 0, 0)
; __device__ __forceinline__ void post_phase(const Params& p, int j, u16* Y, const u16* V, const u16* YB) {
;     ...
;       _Pragma("unroll") for (int m = 0; m < 4; ++m) {
;         int ch0 = hd * 64 + m * 16;
;         f32x4 g = {0.f, 0.f, 0.f, 0.f};
;         _Pragma("unroll") for (int ks = 0; ks < 5; ++ks) g = MFMA16(ga[m][ks], gb[ks], g);
;         float4 lg4 = *reinterpret_cast<const float4*>(lg + ch0 + fq * 4);
;         float4 lb4 = *reinterpret_cast<const float4*>(lb + ch0 + fq * 4);
;         float vv0 = b2f((u16)(vr[m].x & 0xffffu)), vv1 = b2f((u16)(vr[m].x >> 16));
;         float vv2 = b2f((u16)(vr[m].y & 0xffffu)), vv3 = b2f((u16)(vr[m].y >> 16));
;         float o0 = ((yv[m][0] - mu) * rsd * lg4.x + lb4.x + bonus * vv0) * g[0];
;         float o1 = ((yv[m][1] - mu) * rsd * lg4.y + lb4.y + bonus * vv1) * g[1];
;         float o2 = ((yv[m][2] - mu) * rsd * lg4.z + lb4.z + bonus * vv2) * g[2];
;         float o3 = ((yv[m][3] - mu) * rsd * lg4.w + lb4.w + bonus * vv3) * g[3];
;         uint2 o; o.x = pk2(o0, o1); o.y = pk2(o2, o3);
;         *reinterpret_cast<uint2*>(Y + (size_t)tok * CM + ch0 + fq * 4) = o;
	v_lshlrev_b32_e32 v78, 16, v145
	v_and_b32_e32 v79, 0xffff0000, v145
	v_mfma_f32_16x16x32_bf16 v[60:63], v[60:63], v[12:15], v[64:67]
	s_waitcnt lgkmcnt(0)
	v_add_f32_e32 v75, v74, v75
	ds_bpermute_b32 v145, v193, v75
	v_mfma_f32_16x16x32_bf16 v[56:59], v[56:59], v[8:11], v[60:63]
	v_add_f32_e32 v74, v78, v79
	v_lshlrev_b32_e32 v78, 16, v156
	v_and_b32_e32 v79, 0xffff0000, v156
	s_waitcnt lgkmcnt(0)
	v_add_f32_e32 v64, v75, v145
	v_fmamk_f32 v64, v64, 0x3c800000, v184
	v_mul_f32_e32 v65, 0x4b800000, v64
	v_cmp_gt_f32_e32 vcc, s3, v64
	v_mfma_f32_16x16x32_bf16 v[16:19], v[52:55], v[16:19], 0
	v_readlane_b32 s3, v246, 17
	v_cndmask_b32_e32 v64, v64, v65, vcc
	v_rsq_f32_e32 v66, v64
	v_lshlrev_b32_e32 v64, 16, v157
	v_and_b32_e32 v65, 0xffff0000, v157
	v_mfma_f32_16x16x32_bf16 v[12:15], v[48:51], v[12:15], v[16:19]
	v_mul_f32_e32 v60, 0x45800000, v66
	v_cndmask_b32_e32 v60, v66, v60, vcc
	v_pk_mul_f32 v[62:63], v[76:77], v[60:61] op_sel_hi:[1,0]
	v_pk_mul_f32 v[66:67], v[92:93], v[60:61] op_sel_hi:[1,0]
	s_waitcnt vmcnt(6)
	v_pk_fma_f32 v[62:63], v[84:85], v[62:63], v[88:89]
	v_pk_fma_f32 v[66:67], v[86:87], v[66:67], v[90:91]
	v_pk_fma_f32 v[62:63], v[74:75], v[78:79], v[62:63] op_sel_hi:[0,1,1]
	v_pk_fma_f32 v[64:65], v[74:75], v[64:65], v[66:67] op_sel_hi:[0,1,1]
	v_pk_mul_f32 v[62:63], v[80:81], v[62:63]
	v_pk_mul_f32 v[64:65], v[82:83], v[64:65]
	v_cvt_pk_bf16_f32 v62, v62, v63
	v_cvt_pk_bf16_f32 v63, v64, v65
	global_store_dwordx2 v[146:147], v[62:63], off
	s_nop 0
	s_nop 0
	v_mfma_f32_16x16x32_bf16 v[40:43], v[40:43], v[4:7], v[68:71]
	v_lshlrev_b32_e32 v48, 16, v150
	v_and_b32_e32 v49, 0xffff0000, v150
	v_lshlrev_b32_e32 v50, 16, v151
	v_mfma_f32_16x16x32_bf16 v[32:35], v[32:35], v[0:3], v[40:43]
	v_and_b32_e32 v51, 0xffff0000, v151
	v_add_u32_e32 v144, s3, v144
	s_nop 1
	v_pk_mul_f32 v[40:41], v[168:169], v[60:61] op_sel_hi:[1,0]
	v_pk_mul_f32 v[42:43], v[164:165], v[60:61] op_sel_hi:[1,0]
	v_mfma_f32_16x16x32_bf16 v[8:11], v[28:31], v[8:11], v[12:15]
	s_waitcnt vmcnt(5)
	v_pk_fma_f32 v[16:17], v[202:203], v[40:41], v[206:207]
	v_pk_fma_f32 v[18:19], v[204:205], v[42:43], v[208:209] op_sel:[0,1,0] op_sel_hi:[1,0,1]
	v_pk_fma_f32 v[16:17], v[74:75], v[48:49], v[16:17] op_sel_hi:[0,1,1]
	v_pk_fma_f32 v[18:19], v[74:75], v[50:51], v[18:19] op_sel_hi:[0,1,1]
	v_pk_mul_f32 v[16:17], v[32:33], v[16:17]
	v_pk_mul_f32 v[18:19], v[34:35], v[18:19]
	v_cvt_pk_bf16_f32 v16, v16, v17
	v_cvt_pk_bf16_f32 v17, v18, v19
	global_store_dwordx2 v[146:147], v[16:17], off offset:32
	s_nop 0
	s_nop 0
	s_nop 0
	v_mfma_f32_16x16x32_bf16 v[40:43], v[44:47], v[4:7], v[56:59]
	v_lshlrev_b32_e32 v48, 16, v152
	v_and_b32_e32 v49, 0xffff0000, v152
	v_lshlrev_b32_e32 v44, 16, v153
	v_mfma_f32_16x16x32_bf16 v[36:39], v[36:39], v[0:3], v[40:43]
	v_and_b32_e32 v45, 0xffff0000, v153
	v_lshlrev_b32_e32 v12, 16, v148
	v_and_b32_e32 v13, 0xffff0000, v148
	s_nop 0
	v_pk_mul_f32 v[40:41], v[98:99], v[60:61] op_sel_hi:[1,0]
	v_pk_mul_f32 v[42:43], v[72:73], v[60:61] op_sel_hi:[1,0]
	v_mfma_f32_16x16x32_bf16 v[4:7], v[24:27], v[4:7], v[8:11]
	v_lshlrev_b32_e32 v14, 16, v149
	v_and_b32_e32 v15, 0xffff0000, v149
	s_waitcnt vmcnt(4)
	v_pk_fma_f32 v[16:17], v[40:41], v[210:211], v[214:215]
	v_pk_fma_f32 v[18:19], v[42:43], v[212:213], v[216:217]
	v_pk_fma_f32 v[16:17], v[74:75], v[48:49], v[16:17] op_sel_hi:[0,1,1]
	v_pk_fma_f32 v[18:19], v[74:75], v[44:45], v[18:19] op_sel_hi:[0,1,1]
	v_pk_mul_f32 v[16:17], v[36:37], v[16:17]
	v_pk_mul_f32 v[18:19], v[38:39], v[18:19]
	v_cvt_pk_bf16_f32 v16, v16, v17
	v_cvt_pk_bf16_f32 v17, v18, v19
	global_store_dwordx2 v[146:147], v[16:17], off offset:64
	s_nop 0
	s_nop 0
	s_nop 0
	v_mfma_f32_16x16x32_bf16 v[0:3], v[20:23], v[0:3], v[4:7]
	s_nop 2
	v_mul_f32_e64 v4, v94, v60
	v_mul_f32_e64 v5, v95, v60
	v_pk_mul_f32 v[6:7], v[96:97], v[60:61] op_sel_hi:[1,0]
	s_waitcnt vmcnt(3)
	v_pk_fma_f32 v[4:5], v[4:5], v[218:219], v[222:223] op_sel:[1,0,0] op_sel_hi:[0,1,1]
	v_pk_fma_f32 v[6:7], v[6:7], v[220:221], v[224:225] op_sel:[1,0,0] op_sel_hi:[0,1,1]
	v_pk_fma_f32 v[4:5], v[74:75], v[12:13], v[4:5] op_sel_hi:[0,1,1]
	v_pk_fma_f32 v[6:7], v[74:75], v[14:15], v[6:7] op_sel_hi:[0,1,1]
	v_pk_mul_f32 v[0:1], v[0:1], v[4:5]
	v_pk_mul_f32 v[2:3], v[2:3], v[6:7]
	v_cvt_pk_bf16_f32 v0, v0, v1
	v_cvt_pk_bf16_f32 v1, v2, v3
	global_store_dwordx2 v[146:147], v[0:1], off offset:96
	s_cbranch_scc0 .LBB0_2826

; __device__ __forceinline__ float b2f(u16 b) { return __uint_as_float(((unsigned)b) << 16); }
; #define MFMA16(a, b, c) __builtin_amdgcn_mfma_f32_16x16x32_bf16(a, b, c, 0, 0, 0)
; __device__ __forceinline__ void post_phase(const Params& p, int j, u16* Y, const u16* V, const u16* YB) {
;     ...
;       unsigned bw_ = bon[(size_t)tok * 16 + hd];
;       float bonus = b2f((u16)(bw_ & 0xffffu)) + b2f((u16)(bw_ >> 16));
;       float yv[4][4], s1 = 0.f;
;       _Pragma("unroll") for (int m = 0; m < 4; ++m) {
;         yv[m][0] = b2f((u16)(yr[m].x & 0xffffu)) + b2f((u16)(yb2[m].x & 0xffffu)); yv[m][1] = b2f((u16)(yr[m].x >> 16)) + b2f((u16)(yb2[m].x >> 16));
;         yv[m][2] = b2f((u16)(yr[m].y & 0xffffu)) + b2f((u16)(yb2[m].y & 0xffffu)); yv[m][3] = b2f((u16)(yr[m].y >> 16)) + b2f((u16)(yb2[m].y >> 16));
;         s1 += yv[m][0] + yv[m][1] + yv[m][2] + yv[m][3];
;       }
;       s1 += shx(s1, 16, lane); s1 += shx(s1, 32, lane);
;       float mu = s1 * (1.f / 64.f), s2 = 0.f;
;       _Pragma("unroll") for (int m = 0; m < 4; ++m) _Pragma("unroll") for (int e = 0; e < 4; ++e) { float dd = yv[m][e] - mu; s2 += dd * dd; }
;       s2 += shx(s2, 16, lane); s2 += shx(s2, 32, lane);
;       float rsd = rsqrtf(s2 * (1.f / 64.f) + 64e-5f);
;       _Pragma("unroll") for (int m = 0; m < 4; ++m) {
;         int ch0 = hd * 64 + m * 16;
;         f32x4 g = {0.f, 0.f, 0.f, 0.f};
;         _Pragma("unroll") for (int ks = 0; ks < 5; ++ks) g = MFMA16(ga[m][ks], gb[ks], g);
;         float4 lg4 = *reinterpret_cast<const float4*>(lg + ch0 + fq * 4);
;         float4 lb4 = *reinterpret_cast<const float4*>(lb + ch0 + fq * 4);
.LBB0_2818:
	v_lshlrev_b64 v[154:155], 6, v[144:145]
	v_lshl_add_u64 v[154:155], s[0:1], 0, v[154:155]
	v_lshl_add_u64 v[180:181], v[102:103], 2, v[154:155]
	global_load_dword v145, v[180:181], off
	s_waitcnt vmcnt(28)
	v_mfma_f32_16x16x32_bf16 v[96:99], v[96:99], v[16:19], 0
	s_waitcnt vmcnt(16)
	v_lshlrev_b32_e32 v196, 16, v178
	s_waitcnt vmcnt(15)
	v_lshlrev_b32_e32 v198, 16, v172
	v_and_b32_e32 v197, 0xffff0000, v178
	v_mfma_f32_16x16x32_bf16 v[92:95], v[92:95], v[12:15], v[96:99]
	v_and_b32_e32 v199, 0xffff0000, v172
	v_lshlrev_b32_e32 v180, 16, v174
	v_lshlrev_b32_e32 v194, 16, v176
	v_mfma_f32_16x16x32_bf16 v[88:91], v[88:91], v[8:11], v[92:95]
	v_and_b32_e32 v181, 0xffff0000, v174
	v_and_b32_e32 v195, 0xffff0000, v176
	v_lshlrev_b32_e32 v174, 16, v175
	v_mfma_f32_16x16x32_bf16 v[84:87], v[84:87], v[4:7], v[88:91]
	v_lshlrev_b32_e32 v176, 16, v177
	v_and_b32_e32 v175, 0xffff0000, v175
	v_and_b32_e32 v177, 0xffff0000, v177
	v_mfma_f32_16x16x32_bf16 v[80:83], v[80:83], v[0:3], v[84:87]
	s_nop 3
	global_load_dwordx4 v[84:87], v[120:121], off
	global_load_dwordx4 v[88:91], v[122:123], off
	global_load_dwordx4 v[202:205], v[120:121], off offset:64
	global_load_dwordx4 v[206:209], v[122:123], off offset:64
	global_load_dwordx4 v[210:213], v[120:121], off offset:128
	global_load_dwordx4 v[214:217], v[122:123], off offset:128
	global_load_dwordx4 v[218:221], v[120:121], off offset:192
	global_load_dwordx4 v[222:225], v[122:123], off offset:192
	v_pk_add_f32 v[196:197], v[196:197], v[198:199]
	v_lshlrev_b32_e32 v199, 16, v179
	v_lshlrev_b32_e32 v201, 16, v173
	v_and_b32_e32 v198, 0xffff0000, v179
	v_and_b32_e32 v200, 0xffff0000, v173
	v_pk_add_f32 v[172:173], v[198:199], v[200:201]
	v_pk_add_f32 v[178:179], v[196:197], v[196:197] op_sel:[0,1] op_sel_hi:[1,0]
	v_pk_add_f32 v[174:175], v[174:175], v[176:177]
	v_pk_add_f32 v[176:177], v[180:181], v[194:195]
	v_pk_add_f32 v[178:179], v[178:179], v[172:173] op_sel:[0,1] op_sel_hi:[1,0]
	v_add_f32_e32 v94, v176, v177
	v_pk_add_f32 v[96:97], v[172:173], v[178:179]
	s_waitcnt vmcnt(16)
	v_lshlrev_b32_e32 v98, 16, v168
	v_lshlrev_b32_e32 v178, 16, v164
	v_and_b32_e32 v99, 0xffff0000, v168
	v_and_b32_e32 v179, 0xffff0000, v164
	v_add_f32_e32 v94, v94, v174
	v_add_f32_e32 v94, v175, v94
	v_pk_add_f32 v[98:99], v[178:179], v[98:99]
	v_and_b32_e32 v92, 0xffff0000, v169
	s_waitcnt vmcnt(9)
	v_and_b32_e32 v95, 0xffff0000, v166
	v_lshlrev_b32_e32 v93, 16, v167
	v_and_b32_e32 v97, 0xffff0000, v167
	v_add_f32_e32 v164, 0, v94
	v_lshlrev_b32_e32 v181, 16, v170
	v_lshlrev_b32_e32 v180, 16, v165
	v_lshlrev_b32_e32 v167, 16, v166
	v_lshlrev_b32_e32 v166, 16, v169
	v_and_b32_e32 v169, 0xffff0000, v170
	v_mov_b32_e32 v168, v98
	v_mov_b32_e32 v94, v99
	v_pk_add_f32 v[166:167], v[180:181], v[166:167]
	v_and_b32_e32 v180, 0xffff0000, v165
	v_lshlrev_b32_e32 v181, 16, v171
	v_and_b32_e32 v165, 0xffff0000, v171
	v_pk_add_f32 v[94:95], v[168:169], v[94:95]
	v_pk_add_f32 v[92:93], v[180:181], v[92:93]
	v_pk_add_f32 v[96:97], v[164:165], v[96:97]
	v_pk_add_f32 v[164:165], v[166:167], v[94:95]
	v_mfma_f32_16x16x32_bf16 v[76:79], v[76:79], v[16:19], 0
	v_add_f32_e64 v164, v164, v92
	v_add_f32_e64 v165, v165, v93
	s_mov_b32 s3, 0x800000
	v_pk_add_f32 v[164:165], v[96:97], v[164:165]
	v_mfma_f32_16x16x32_bf16 v[72:75], v[72:75], v[12:15], v[76:79]
	v_add_f32_e32 v94, v164, v165
	ds_bpermute_b32 v164, v128, v94
	v_mov_b32_e32 v96, v97
	v_mfma_f32_16x16x32_bf16 v[68:71], v[68:71], v[8:11], v[72:75]
	v_mov_b32_e32 v97, v93
	s_waitcnt lgkmcnt(0)
	v_add_f32_e32 v76, v94, v164
	ds_bpermute_b32 v77, v193, v76
	v_mov_b32_e32 v73, v92
	v_mov_b32_e32 v72, v166
	v_mov_b32_e32 v166, v95
	v_mfma_f32_16x16x32_bf16 v[64:67], v[64:67], v[16:19], 0
	s_waitcnt lgkmcnt(0)
	v_add_f32_e32 v74, v76, v77
	v_mul_f32_e32 v74, 0x3c800000, v74
	v_pk_add_f32 v[76:77], v[176:177], v[74:75] op_sel_hi:[1,0] neg_lo:[0,1] neg_hi:[0,1]
	v_pk_add_f32 v[92:93], v[174:175], v[74:75] op_sel_hi:[1,0] neg_lo:[0,1] neg_hi:[0,1]
	v_pk_mul_f32 v[78:79], v[76:77], v[76:77]
	v_pk_mul_f32 v[164:165], v[92:93], v[92:93]
	v_add_f32_e32 v78, v78, v79
	v_pk_add_f32 v[176:177], v[196:197], v[74:75] op_sel_hi:[1,0] neg_lo:[0,1] neg_hi:[0,1]
	v_add_f32_e32 v78, v164, v78
	v_pk_mul_f32 v[178:179], v[176:177], v[176:177]
	v_add_f32_e32 v78, v165, v78
	v_pk_add_f32 v[172:173], v[172:173], v[74:75] op_sel_hi:[1,0] neg_lo:[0,1] neg_hi:[0,1]
	v_add_f32_e32 v78, v178, v78
	v_pk_mul_f32 v[174:175], v[172:173], v[172:173]
	v_add_f32_e32 v78, v179, v78
	v_pk_add_f32 v[98:99], v[98:99], v[74:75] op_sel_hi:[1,0] neg_lo:[0,1] neg_hi:[0,1]
	v_add_f32_e32 v78, v175, v78
	v_pk_mul_f32 v[168:169], v[98:99], v[98:99]
	v_add_f32_e32 v78, v174, v78
	v_pk_add_f32 v[72:73], v[72:73], v[74:75] op_sel_hi:[1,0] neg_lo:[0,1] neg_hi:[0,1]
	v_add_f32_e32 v78, v168, v78
	v_pk_add_f32 v[94:95], v[166:167], v[74:75] op_sel_hi:[1,0] neg_lo:[0,1] neg_hi:[0,1]
	v_pk_add_f32 v[96:97], v[96:97], v[74:75] op_sel_hi:[1,0] neg_lo:[0,1] neg_hi:[0,1]
	v_pk_mul_f32 v[74:75], v[72:73], v[72:73]
	v_add_f32_e32 v78, v169, v78
	v_add_f32_e32 v74, v74, v78
	v_pk_mul_f32 v[166:167], v[94:95], v[94:95]
	v_add_f32_e32 v74, v75, v74
	v_add_f32_e32 v74, v167, v74
	v_pk_mul_f32 v[170:171], v[96:97], v[96:97]
	v_add_f32_e32 v74, v166, v74
	v_add_f32_e32 v74, v171, v74
	v_add_f32_e32 v74, v170, v74
	ds_bpermute_b32 v75, v128, v74
	s_waitcnt vmcnt(8)
; __device__ __forceinline__ unsigned pk2(float a, float b) { f2_t x; x[0] = a; x[1] = b; return __builtin_bit_cast(unsigned, __builtin_convertvector(x, bf2_t)); }
; __device__ __forceinline__ float b2f(u16 b) { return __uint_as_float(((unsigned)b) << 16); }
; #define MFMA16(a, b, c) __builtin_amdgcn_mfma_f32_16x16x32_bf16(a, b, c, 0, 0, 0)
; __device__ __forceinline__ void post_phase(const Params& p, int j, u16* Y, const u16* V, const u16* YB) {
;     ...
;     _Pragma("unroll") for (int ks = 0; ks < 5; ++ks) gb[ks] = ld8(gmid + (size_t)tok * 160 + ks * 32 + fq * 8);
;     _Pragma("unroll") for (int hh = 0; hh < 2; ++hh) {
;       int hd = wv * 2 + hh;
;       bf16x8 ga[4][5]; uint2 yr[4], vr[4], yb2[4];
;       _Pragma("unroll") for (int m = 0; m < 4; ++m) {
;         int ch0 = hd * 64 + m * 16;
;         _Pragma("unroll") for (int ks = 0; ks < 5; ++ks) ga[m][ks] = ld8(g2T + (size_t)(ch0 + fr) * 160 + ks * 32 + fq * 8);
;         yr[m] = *reinterpret_cast<const uint2*>(Y + (size_t)tok * CM + ch0 + fq * 4);
;         vr[m] = *reinterpret_cast<const uint2*>(V + (size_t)tok * CM + ch0 + fq * 4);
;         yb2[m] = sample ? *reinterpret_cast<const uint2*>(YB + (size_t)(tok - NPROMPT) * CM + ch0 + fq * 4) : make_uint2(0u, 0u);
;     ...
;       _Pragma("unroll") for (int m = 0; m < 4; ++m) {
;         int ch0 = hd * 64 + m * 16;
;         f32x4 g = {0.f, 0.f, 0.f, 0.f};
;         _Pragma("unroll") for (int ks = 0; ks < 5; ++ks) g = MFMA16(ga[m][ks], gb[ks], g);
;         float4 lg4 = *reinterpret_cast<const float4*>(lg + ch0 + fq * 4);
;         float4 lb4 = *reinterpret_cast<const float4*>(lb + ch0 + fq * 4);
;         float vv0 = b2f((u16)(vr[m].x & 0xffffu)), vv1 = b2f((u16)(vr[m].x >> 16));
;         float vv2 = b2f((u16)(vr[m].y & 0xffffu)), vv3 = b2f((u16)(vr[m].y >> 16));
;         float o0 = ((yv[m][0] - mu) * rsd * lg4.x + lb4.x + bonus * vv0) * g[0];
;         float o1 = ((yv[m][1] - mu) * rsd * lg4.y + lb4.y + bonus * vv1) * g[1];
;         float o2 = ((yv[m][2] - mu) * rsd * lg4.z + lb4.z + bonus * vv2) * g[2];
;         float o3 = ((yv[m][3] - mu) * rsd * lg4.w + lb4.w + bonus * vv3) * g[3];
;         uint2 o; o.x = pk2(o0, o1); o.y = pk2(o2, o3);
;         *reinterpret_cast<uint2*>(Y + (size_t)tok * CM + ch0 + fq * 4) = o;
	v_lshlrev_b32_e32 v78, 16, v145
	v_and_b32_e32 v79, 0xffff0000, v145
	v_mfma_f32_16x16x32_bf16 v[60:63], v[60:63], v[12:15], v[64:67]
	v_mov_b32_e32 v168, 0
	s_waitcnt lgkmcnt(0)
	v_add_f32_e32 v75, v74, v75
	ds_bpermute_b32 v145, v193, v75
	v_mfma_f32_16x16x32_bf16 v[56:59], v[56:59], v[8:11], v[60:63]
	v_add_f32_e32 v74, v78, v79
	v_lshlrev_b32_e32 v78, 16, v162
	v_and_b32_e32 v79, 0xffff0000, v162
	s_waitcnt lgkmcnt(0)
	v_add_f32_e32 v64, v75, v145
	v_fmamk_f32 v64, v64, 0x3c800000, v184
	v_mul_f32_e32 v65, 0x4b800000, v64
	v_cmp_gt_f32_e32 vcc, s3, v64
	v_mfma_f32_16x16x32_bf16 v[52:55], v[52:55], v[16:19], 0
	v_lshl_add_u64 v[174:175], v[126:127], 1, v[152:153]
	v_cndmask_b32_e32 v64, v64, v65, vcc
	v_rsq_f32_e32 v66, v64
	v_lshlrev_b32_e32 v64, 16, v163
	v_and_b32_e32 v65, 0xffff0000, v163
	v_mfma_f32_16x16x32_bf16 v[48:51], v[48:51], v[12:15], v[52:55]
	v_mul_f32_e32 v60, 0x45800000, v66
	v_cndmask_b32_e32 v66, v66, v60, vcc
	v_pk_mul_f32 v[60:61], v[76:77], v[66:67] op_sel_hi:[1,0]
	v_pk_mul_f32 v[62:63], v[92:93], v[66:67] op_sel_hi:[1,0]
	s_waitcnt vmcnt(6)
	v_pk_fma_f32 v[60:61], v[84:85], v[60:61], v[88:89]
	v_pk_fma_f32 v[62:63], v[86:87], v[62:63], v[90:91]
	v_pk_fma_f32 v[60:61], v[74:75], v[78:79], v[60:61] op_sel_hi:[0,1,1]
	v_pk_fma_f32 v[62:63], v[74:75], v[64:65], v[62:63] op_sel_hi:[0,1,1]
	v_pk_mul_f32 v[60:61], v[80:81], v[60:61]
	v_pk_mul_f32 v[62:63], v[82:83], v[62:63]
	v_cvt_pk_bf16_f32 v60, v60, v61
	v_cvt_pk_bf16_f32 v61, v62, v63
	global_store_dwordx2 v[150:151], v[60:61], off
	s_nop 0
	v_mfma_f32_16x16x32_bf16 v[36:39], v[36:39], v[4:7], v[68:71]
	s_nop 0
	v_lshlrev_b32_e32 v64, 16, v158
	v_and_b32_e32 v65, 0xffff0000, v158
	v_mfma_f32_16x16x32_bf16 v[32:35], v[32:35], v[0:3], v[36:39]
	v_lshlrev_b32_e32 v68, 16, v159
	v_and_b32_e32 v69, 0xffff0000, v159
	s_and_b64 vcc, exec, s[4:5]
	s_nop 0
	v_pk_mul_f32 v[36:37], v[176:177], v[66:67] op_sel_hi:[1,0]
	v_pk_mul_f32 v[38:39], v[172:173], v[66:67] op_sel_hi:[1,0]
	v_mfma_f32_16x16x32_bf16 v[44:47], v[44:47], v[4:7], v[56:59]
	v_mov_b32_e32 v170, 0
	v_mov_b32_e32 v171, 0
	s_waitcnt vmcnt(5)
	v_pk_fma_f32 v[36:37], v[202:203], v[36:37], v[206:207]
	v_pk_fma_f32 v[38:39], v[204:205], v[38:39], v[208:209] op_sel:[0,1,0] op_sel_hi:[1,0,1]
	v_pk_fma_f32 v[36:37], v[74:75], v[64:65], v[36:37] op_sel_hi:[0,1,1]
	v_pk_fma_f32 v[38:39], v[74:75], v[68:69], v[38:39] op_sel_hi:[0,1,1]
	v_pk_mul_f32 v[32:33], v[32:33], v[36:37]
	v_pk_mul_f32 v[34:35], v[34:35], v[38:39]
	v_cvt_pk_bf16_f32 v32, v32, v33
	v_cvt_pk_bf16_f32 v33, v34, v35
	global_store_dwordx2 v[150:151], v[32:33], off offset:32
	s_nop 0
	s_nop 0
	s_nop 0
	v_mfma_f32_16x16x32_bf16 v[40:43], v[40:43], v[0:3], v[44:47]
	v_lshlrev_b32_e32 v52, 16, v160
	v_and_b32_e32 v53, 0xffff0000, v160
	v_lshlrev_b32_e32 v54, 16, v161
	v_pk_mul_f32 v[44:45], v[98:99], v[66:67] op_sel_hi:[1,0]
	v_pk_mul_f32 v[46:47], v[72:73], v[66:67] op_sel_hi:[1,0]
	v_and_b32_e32 v55, 0xffff0000, v161
	v_mfma_f32_16x16x32_bf16 v[28:31], v[28:31], v[8:11], v[48:51]
	s_waitcnt vmcnt(4)
	v_pk_fma_f32 v[32:33], v[44:45], v[210:211], v[214:215]
	v_pk_fma_f32 v[34:35], v[46:47], v[212:213], v[216:217]
	v_pk_fma_f32 v[32:33], v[74:75], v[52:53], v[32:33] op_sel_hi:[0,1,1]
	v_pk_fma_f32 v[34:35], v[74:75], v[54:55], v[34:35] op_sel_hi:[0,1,1]
	v_pk_mul_f32 v[32:33], v[40:41], v[32:33]
	v_pk_mul_f32 v[34:35], v[42:43], v[34:35]
	v_cvt_pk_bf16_f32 v32, v32, v33
	v_cvt_pk_bf16_f32 v33, v34, v35
	global_store_dwordx2 v[150:151], v[32:33], off offset:64
	s_nop 0
	s_nop 0
	s_nop 0
	v_mfma_f32_16x16x32_bf16 v[24:27], v[24:27], v[4:7], v[28:31]
	v_lshlrev_b32_e32 v40, 16, v156
	v_and_b32_e32 v41, 0xffff0000, v156
	v_lshlrev_b32_e32 v42, 16, v157
	v_mfma_f32_16x16x32_bf16 v[20:23], v[20:23], v[0:3], v[24:27]
	v_and_b32_e32 v43, 0xffff0000, v157
	v_lshlrev_b64 v[44:45], 1, v[126:127]
	v_lshl_add_u64 v[146:147], v[146:147], 0, v[44:45]
	s_nop 0
	v_pk_mul_f32 v[24:25], v[94:95], v[66:67] op_sel_hi:[1,0]
	v_pk_mul_f32 v[26:27], v[96:97], v[66:67] op_sel_hi:[1,0]
	v_lshl_add_u64 v[148:149], v[148:149], 0, v[44:45]
	global_load_dwordx2 v[166:167], v[146:147], off
	s_waitcnt vmcnt(4)
	v_pk_fma_f32 v[24:25], v[24:25], v[218:219], v[222:223] op_sel:[1,0,0] op_sel_hi:[0,1,1]
	v_pk_fma_f32 v[26:27], v[26:27], v[220:221], v[224:225] op_sel:[1,0,0] op_sel_hi:[0,1,1]
	v_pk_fma_f32 v[24:25], v[74:75], v[40:41], v[24:25] op_sel_hi:[0,1,1]
	v_pk_fma_f32 v[26:27], v[74:75], v[42:43], v[26:27] op_sel_hi:[0,1,1]
	v_pk_mul_f32 v[20:21], v[20:21], v[24:25]
	v_pk_mul_f32 v[22:23], v[22:23], v[26:27]
	v_cvt_pk_bf16_f32 v20, v20, v21
	v_cvt_pk_bf16_f32 v21, v22, v23
	global_store_dwordx2 v[150:151], v[20:21], off offset:96
	global_load_dwordx4 v[96:99], v[132:133], off
	global_load_dwordx4 v[92:95], v[132:133], off offset:64
	global_load_dwordx4 v[88:91], v[132:133], off offset:128
	global_load_dwordx4 v[84:87], v[132:133], off offset:192
	global_load_dwordx4 v[80:83], v[132:133], off offset:256
	global_load_dwordx2 v[156:157], v[148:149], off
	s_cbranch_vccnz .LBB0_2820
	global_load_dwordx2 v[170:171], v[174:175], off
